# scan patch + attention: next-tile K/V loads issued at half-step start
# speedup vs baseline: 1.0001x; 1.0001x over previous
.LBB0_474:
	v_add_u32_e32 v146, s51, v165
	v_add_u32_e32 v140, 1, v146
	v_add_u32_e32 v142, 33, v146
	v_mad_i64_i32 v[132:133], s[2:3], v140, s15, v[168:169]
	v_mad_i64_i32 v[136:137], s[2:3], v142, s15, v[168:169]
	v_mad_i64_i32 v[140:141], s[2:3], v140, s15, v[170:171]
	v_mad_i64_i32 v[144:145], s[2:3], v142, s15, v[170:171]
	global_load_dwordx4 v[132:135], v[132:133], off
	s_nop 0
	global_load_dwordx4 v[136:139], v[136:137], off
	s_nop 0
	global_load_dwordx4 v[140:143], v[140:141], off
	s_nop 0
	global_load_dwordx4 v[144:147], v[144:145], off
	s_cmp_eq_u64 s[28:29], 0
	s_cbranch_scc1 .Lfox_h1_skip
	s_add_i32 s2, s51, 1
	s_ashr_i32 s3, s2, 31
	v_lshl_add_u64 v[220:221], s[2:3], 2, v[172:173]
	s_add_i32 m0, 0, 0x10800
	s_nop 0
	global_load_lds_dword v[220:221], off
.Lfox_h1_skip:
	ds_read_b128 v[66:69], v189 offset:49152
	ds_read_b128 v[70:73], v189 offset:57344
	ds_read_b128 v[74:77], v185
	ds_read_b128 v[98:101], v188 offset:49152
	ds_read_b128 v[102:105], v188 offset:57344
	ds_read_b128 v[106:109], v185 offset:1024
	v_exp_f32_e32 v110, v158
	v_exp_f32_e32 v111, v159
	v_exp_f32_e32 v112, v156
	s_waitcnt lgkmcnt(3)
	v_mfma_f32_32x32x16_bf16 v[82:97], v[66:69], v[74:77], 0
	v_exp_f32_e32 v113, v157
	v_exp_f32_e32 v114, v154
	v_exp_f32_e32 v115, v155
	v_exp_f32_e32 v116, v152
	v_exp_f32_e32 v117, v153
	v_exp_f32_e32 v118, v150
	v_exp_f32_e32 v119, v151
	v_mfma_f32_32x32x16_bf16 v[66:81], v[70:73], v[74:77], 0
	v_exp_f32_e32 v120, v148
	v_exp_f32_e32 v121, v149
	s_waitcnt lgkmcnt(0)
	v_mfma_f32_32x32x16_bf16 v[82:97], v[98:101], v[106:109], v[82:97]
	v_mfma_f32_32x32x16_bf16 v[66:81], v[102:105], v[106:109], v[66:81]
	ds_read_b128 v[98:101], v187 offset:49152
	ds_read_b128 v[102:105], v187 offset:57344
	ds_read_b128 v[106:109], v185 offset:2048
	s_waitcnt lgkmcnt(0)
	v_mfma_f32_32x32x16_bf16 v[82:97], v[98:101], v[106:109], v[82:97]
	v_mfma_f32_32x32x16_bf16 v[66:81], v[102:105], v[106:109], v[66:81]
	ds_read_b128 v[98:101], v186 offset:49152
	ds_read_b128 v[102:105], v186 offset:57344
	ds_read_b128 v[106:109], v185 offset:3072
	s_waitcnt lgkmcnt(0)
	v_mfma_f32_32x32x16_bf16 v[82:97], v[98:101], v[106:109], v[82:97]
	v_mfma_f32_32x32x16_bf16 v[66:81], v[102:105], v[106:109], v[66:81]
	ds_read_b128 v[98:101], v189 offset:49280
	ds_read_b128 v[102:105], v189 offset:57472
	ds_read_b128 v[106:109], v185 offset:4096
	s_waitcnt lgkmcnt(0)
	v_mfma_f32_32x32x16_bf16 v[82:97], v[98:101], v[106:109], v[82:97]
	v_mfma_f32_32x32x16_bf16 v[66:81], v[102:105], v[106:109], v[66:81]
	ds_read_b128 v[98:101], v188 offset:49280
	ds_read_b128 v[102:105], v188 offset:57472
	ds_read_b128 v[106:109], v185 offset:5120
	s_waitcnt lgkmcnt(0)
	v_mfma_f32_32x32x16_bf16 v[82:97], v[98:101], v[106:109], v[82:97]
	v_mfma_f32_32x32x16_bf16 v[66:81], v[102:105], v[106:109], v[66:81]
	ds_read_b128 v[98:101], v187 offset:49280
	ds_read_b128 v[102:105], v187 offset:57472
	ds_read_b128 v[106:109], v185 offset:6144
	s_waitcnt lgkmcnt(0)
	v_mfma_f32_32x32x16_bf16 v[82:97], v[98:101], v[106:109], v[82:97]
	v_mfma_f32_32x32x16_bf16 v[66:81], v[102:105], v[106:109], v[66:81]
	ds_read_b128 v[98:101], v186 offset:49280
	ds_read_b128 v[102:105], v186 offset:57472
	ds_read_b128 v[106:109], v185 offset:7168
	s_waitcnt lgkmcnt(0)
	v_mfma_f32_32x32x16_bf16 v[82:97], v[98:101], v[106:109], v[82:97]
	v_add_f32_e32 v98, 0, v207
	v_add_f32_e32 v98, v208, v98
	v_add_f32_e32 v98, v209, v98
	v_add_f32_e32 v98, v211, v98
	v_add_f32_e32 v98, v212, v98
	v_add_f32_e32 v98, v216, v98
	v_add_f32_e32 v98, v210, v98
	v_add_f32_e32 v98, v213, v98
	v_add_f32_e32 v98, v199, v98
	v_add_f32_e32 v98, v201, v98
	v_add_f32_e32 v98, v202, v98
	v_add_f32_e32 v98, v203, v98
	v_mfma_f32_32x32x16_bf16 v[66:81], v[102:105], v[106:109], v[66:81]
	v_exp_f32_e32 v106, v162
	v_add_f32_e32 v98, v200, v98
	v_exp_f32_e32 v107, v163
	v_add_f32_e32 v98, v204, v98
	v_exp_f32_e32 v108, v160
	v_add_f32_e32 v98, v205, v98
	v_exp_f32_e32 v109, v161
	v_add_f32_e32 v98, v206, v98
	v_add_f32_e32 v98, v106, v98
	v_add_f32_e32 v98, v107, v98
	v_add_f32_e32 v98, v108, v98
	v_add_f32_e32 v98, v109, v98
	v_add_f32_e32 v98, v110, v98
	v_add_f32_e32 v98, v111, v98
	v_add_f32_e32 v98, v112, v98
	v_add_f32_e32 v98, v113, v98
	v_add_f32_e32 v98, v114, v98
	v_add_f32_e32 v98, v115, v98
	v_add_f32_e32 v98, v116, v98
	v_add_f32_e32 v98, v117, v98
	v_add_f32_e32 v98, v118, v98
	v_add_f32_e32 v98, v119, v98
	v_add_f32_e32 v98, v120, v98
	v_add_f32_e32 v196, v121, v98
	v_mov_b32_e32 v197, v196
	v_cvt_pk_bf16_f32 v98, v207, v208
	v_cvt_pk_bf16_f32 v99, v209, v211
	v_cvt_pk_bf16_f32 v100, v212, v216
	v_cvt_pk_bf16_f32 v101, v210, v213
	v_cvt_pk_bf16_f32 v102, v199, v201
	v_cvt_pk_bf16_f32 v103, v202, v203
	v_cvt_pk_bf16_f32 v104, v200, v204
	v_cvt_pk_bf16_f32 v105, v205, v206
	v_cvt_pk_bf16_f32 v106, v106, v107
	v_cvt_pk_bf16_f32 v107, v108, v109
	v_cvt_pk_bf16_f32 v108, v110, v111
	v_cvt_pk_bf16_f32 v109, v112, v113
	v_cvt_pk_bf16_f32 v110, v114, v115
	v_cvt_pk_bf16_f32 v111, v116, v117
	v_cvt_pk_bf16_f32 v112, v118, v119
	v_cvt_pk_bf16_f32 v113, v120, v121
	v_permlane32_swap_b32_e32 v196, v197
	v_permlane32_swap_b32_e32 v98, v100
	v_permlane32_swap_b32_e32 v99, v101
	v_permlane32_swap_b32_e32 v102, v104
	v_permlane32_swap_b32_e32 v103, v105
	v_permlane32_swap_b32_e32 v106, v108
	v_permlane32_swap_b32_e32 v107, v109
	v_permlane32_swap_b32_e32 v110, v112
	v_permlane32_swap_b32_e32 v111, v113
	v_add_u32_e32 v199, s51, v165
	v_cndmask_b32_e64 v114, 0, 1, s[28:29]
	v_cmp_ne_u32_e64 s[44:45], 1, v114

.LBB0_482:
	v_cndmask_b32_e64 v194, v78, v194, s[2:3]
	v_mul_f32_e32 v148, 0xbe0293ee, v194
	v_fmamk_f32 v78, v100, 0x3e0293ee, v148
	v_fmamk_f32 v79, v101, 0x3e0293ee, v148
	v_fmamk_f32 v80, v96, 0x3e0293ee, v148
	v_fmamk_f32 v81, v97, 0x3e0293ee, v148
	v_fmamk_f32 v98, v98, 0x3e0293ee, v148
	v_fmamk_f32 v99, v99, 0x3e0293ee, v148
	v_fmamk_f32 v100, v88, 0x3e0293ee, v148
	v_fmamk_f32 v101, v89, 0x3e0293ee, v148
	v_fmamk_f32 v102, v90, 0x3e0293ee, v148
	v_fmamk_f32 v103, v91, 0x3e0293ee, v148
	v_fmamk_f32 v104, v92, 0x3e0293ee, v148
	v_fmamk_f32 v105, v93, 0x3e0293ee, v148
	v_fmamk_f32 v106, v94, 0x3e0293ee, v148
	v_fmamk_f32 v107, v95, 0x3e0293ee, v148
	v_fmamk_f32 v108, v86, 0x3e0293ee, v148
	v_fmamk_f32 v109, v87, 0x3e0293ee, v148
	v_fmamk_f32 v86, v66, 0x3e0293ee, v148
	v_fmamk_f32 v95, v67, 0x3e0293ee, v148
	v_fmamk_f32 v96, v68, 0x3e0293ee, v148
	v_fmamk_f32 v97, v69, 0x3e0293ee, v148
	v_fmamk_f32 v149, v70, 0x3e0293ee, v148
	v_fmamk_f32 v87, v71, 0x3e0293ee, v148
	v_fmamk_f32 v88, v72, 0x3e0293ee, v148
	v_fmamk_f32 v89, v73, 0x3e0293ee, v148
	v_fmamk_f32 v90, v74, 0x3e0293ee, v148
	v_fmamk_f32 v91, v75, 0x3e0293ee, v148
	v_fmamk_f32 v92, v76, 0x3e0293ee, v148
	v_fmamk_f32 v93, v77, 0x3e0293ee, v148
	v_exp_f32_e32 v66, v78
	v_exp_f32_e32 v67, v79
	v_exp_f32_e32 v68, v80
	v_exp_f32_e32 v69, v81
	v_exp_f32_e32 v70, v98
	v_exp_f32_e32 v71, v99
	v_exp_f32_e32 v72, v100
	v_exp_f32_e32 v73, v101
	v_exp_f32_e32 v74, v102
	v_exp_f32_e32 v75, v103
	v_exp_f32_e32 v76, v104
	v_exp_f32_e32 v77, v105
	v_exp_f32_e32 v78, v106
	v_exp_f32_e32 v79, v107
	v_exp_f32_e32 v80, v108
	v_exp_f32_e32 v81, v109
	v_fmamk_f32 v94, v82, 0x3e0293ee, v148
	v_fmamk_f32 v150, v83, 0x3e0293ee, v148
	v_fmamk_f32 v151, v84, 0x3e0293ee, v148
	v_fmac_f32_e32 v148, 0x3e0293ee, v85
	s_waitcnt lgkmcnt(0)
	s_barrier
	s_add_i32 s34, s27, 1
	s_cmp_ge_i32 s34, s50
	s_cbranch_scc1 .Lfox_h2_skip
	v_add_u32_e32 v140, 0x41, v199
	v_add_u32_e32 v142, 0x61, v199
	v_mad_i64_i32 v[132:133], s[34:35], v140, s15, v[168:169]
	v_mad_i64_i32 v[136:137], s[34:35], v142, s15, v[168:169]
	v_mad_i64_i32 v[140:141], s[34:35], v140, s15, v[170:171]
	v_mad_i64_i32 v[144:145], s[34:35], v142, s15, v[170:171]
	global_load_dwordx4 v[132:135], v[132:133], off
	s_nop 0
	global_load_dwordx4 v[136:139], v[136:137], off
	s_nop 0
	global_load_dwordx4 v[140:143], v[140:141], off
	s_nop 0
	global_load_dwordx4 v[144:147], v[144:145], off
	s_cmp_lg_u64 s[44:45], 0
	s_cbranch_scc1 .Lfox_h2_skip
	s_add_i32 s34, s51, 0x41
	s_ashr_i32 s35, s34, 31
	v_lshl_add_u64 v[200:201], s[34:35], 2, v[172:173]
	v_readlane_b32 s34, v255, 18
	s_mov_b32 m0, s34
	s_nop 0
	global_load_lds_dword v[200:201], off
.Lfox_h2_skip:
	ds_read_b128 v[82:85], v189 offset:32768
	ds_read_b128 v[98:101], v189 offset:40960
	ds_read_b128 v[102:105], v185
	v_exp_f32_e32 v87, v87
	v_exp_f32_e32 v88, v88
	v_exp_f32_e32 v89, v89
	v_exp_f32_e32 v90, v90
	s_waitcnt lgkmcnt(0)
	v_mfma_f32_32x32x16_bf16 v[114:129], v[82:85], v[102:105], 0
	ds_read_b128 v[82:85], v188 offset:32768
	ds_read_b128 v[152:155], v188 offset:40960
	ds_read_b128 v[156:159], v185 offset:1024
	v_exp_f32_e32 v91, v91
	v_exp_f32_e32 v92, v92
	v_exp_f32_e32 v93, v93
	v_exp_f32_e32 v94, v94
	v_cvt_pk_bf16_f32 v160, v90, v91
	v_cvt_pk_bf16_f32 v161, v92, v93
	v_mfma_f32_32x32x16_bf16 v[98:113], v[98:101], v[102:105], 0
	s_waitcnt lgkmcnt(0)
	v_mfma_f32_32x32x16_bf16 v[114:129], v[82:85], v[156:159], v[114:129]
	v_mfma_f32_32x32x16_bf16 v[98:113], v[152:155], v[156:159], v[98:113]
	ds_read_b128 v[82:85], v187 offset:32768
	ds_read_b128 v[152:155], v187 offset:40960
	ds_read_b128 v[156:159], v185 offset:2048
	s_waitcnt lgkmcnt(0)
	v_mfma_f32_32x32x16_bf16 v[114:129], v[82:85], v[156:159], v[114:129]
	v_mfma_f32_32x32x16_bf16 v[98:113], v[152:155], v[156:159], v[98:113]
	ds_read_b128 v[82:85], v186 offset:32768
	ds_read_b128 v[152:155], v186 offset:40960
	ds_read_b128 v[156:159], v185 offset:3072
	s_waitcnt lgkmcnt(0)
	v_mfma_f32_32x32x16_bf16 v[114:129], v[82:85], v[156:159], v[114:129]
	v_mfma_f32_32x32x16_bf16 v[98:113], v[152:155], v[156:159], v[98:113]
	ds_read_b128 v[82:85], v189 offset:32896
	ds_read_b128 v[152:155], v189 offset:41088
	ds_read_b128 v[156:159], v185 offset:4096
	s_waitcnt lgkmcnt(0)
	v_mfma_f32_32x32x16_bf16 v[114:129], v[82:85], v[156:159], v[114:129]
	v_mfma_f32_32x32x16_bf16 v[98:113], v[152:155], v[156:159], v[98:113]
	ds_read_b128 v[82:85], v188 offset:32896
	ds_read_b128 v[152:155], v188 offset:41088
	ds_read_b128 v[156:159], v185 offset:5120
	s_waitcnt lgkmcnt(0)
	v_mfma_f32_32x32x16_bf16 v[114:129], v[82:85], v[156:159], v[114:129]
	v_mfma_f32_32x32x16_bf16 v[98:113], v[152:155], v[156:159], v[98:113]
	ds_read_b128 v[82:85], v187 offset:32896
	ds_read_b128 v[152:155], v187 offset:41088
	ds_read_b128 v[156:159], v185 offset:6144
	s_waitcnt lgkmcnt(0)
	v_mfma_f32_32x32x16_bf16 v[114:129], v[82:85], v[156:159], v[114:129]
	v_mfma_f32_32x32x16_bf16 v[98:113], v[152:155], v[156:159], v[98:113]
	ds_read_b128 v[82:85], v186 offset:32896
	ds_read_b128 v[152:155], v186 offset:41088
	ds_read_b128 v[156:159], v185 offset:7168
	s_waitcnt lgkmcnt(0)
	v_mfma_f32_32x32x16_bf16 v[114:129], v[82:85], v[156:159], v[114:129]
	v_exp_f32_e32 v85, v97
	v_exp_f32_e32 v97, v148
	v_add_f32_e32 v148, 0, v66
	v_add_f32_e32 v148, v67, v148
	v_add_f32_e32 v148, v68, v148
	v_add_f32_e32 v148, v69, v148
	v_add_f32_e32 v148, v70, v148
	v_add_f32_e32 v148, v71, v148
	v_add_f32_e32 v148, v72, v148
	v_add_f32_e32 v148, v73, v148
	v_add_f32_e32 v148, v74, v148
	v_add_f32_e32 v148, v75, v148
	v_add_f32_e32 v148, v76, v148
	v_add_f32_e32 v148, v77, v148
	v_exp_f32_e32 v82, v86
	v_add_f32_e32 v148, v78, v148
	v_exp_f32_e32 v83, v95
	v_add_f32_e32 v148, v79, v148
	v_exp_f32_e32 v84, v96
	v_add_f32_e32 v148, v80, v148
	v_add_f32_e32 v148, v81, v148
	v_exp_f32_e32 v86, v149
	v_add_f32_e32 v148, v82, v148
	v_add_f32_e32 v148, v83, v148
	v_add_f32_e32 v148, v84, v148
	v_add_f32_e32 v148, v85, v148
	v_add_f32_e32 v148, v86, v148
	v_add_f32_e32 v148, v87, v148
	v_add_f32_e32 v148, v88, v148
	v_add_f32_e32 v148, v89, v148
	v_add_f32_e32 v148, v90, v148
	v_exp_f32_e32 v95, v150
	v_add_f32_e32 v148, v91, v148
	v_mfma_f32_32x32x16_bf16 v[98:113], v[152:155], v[156:159], v[98:113]
	v_exp_f32_e32 v96, v151
	v_add_f32_e32 v148, v92, v148
	v_add_f32_e32 v148, v93, v148
	v_add_f32_e32 v148, v94, v148
	v_add_f32_e32 v148, v95, v148
	v_add_f32_e32 v148, v96, v148
	v_add_f32_e32 v217, v97, v148
	v_mov_b32_e32 v218, v217
	v_cvt_pk_bf16_f32 v148, v66, v67
	v_cvt_pk_bf16_f32 v149, v68, v69
	v_cvt_pk_bf16_f32 v150, v70, v71
	v_cvt_pk_bf16_f32 v151, v72, v73
	v_cvt_pk_bf16_f32 v152, v74, v75
	v_cvt_pk_bf16_f32 v153, v76, v77
	v_cvt_pk_bf16_f32 v154, v78, v79
	v_cvt_pk_bf16_f32 v155, v80, v81
	v_cvt_pk_bf16_f32 v156, v82, v83
	v_cvt_pk_bf16_f32 v157, v84, v85
	v_cvt_pk_bf16_f32 v158, v86, v87
	v_cvt_pk_bf16_f32 v159, v88, v89
	v_cvt_pk_bf16_f32 v162, v94, v95
	v_cvt_pk_bf16_f32 v163, v96, v97
	v_permlane32_swap_b32_e32 v217, v218
	v_permlane32_swap_b32_e32 v148, v150
	v_permlane32_swap_b32_e32 v149, v151
	v_permlane32_swap_b32_e32 v152, v154
	v_permlane32_swap_b32_e32 v153, v155
	v_permlane32_swap_b32_e32 v156, v158
	v_permlane32_swap_b32_e32 v157, v159
	v_permlane32_swap_b32_e32 v160, v162
	v_permlane32_swap_b32_e32 v161, v163
	s_add_i32 s34, s27, 1
	s_cmp_lt_i32 s34, s50
	s_cselect_b64 s[2:3], -1, 0
	s_cmp_ge_i32 s34, s50
	s_cbranch_scc1 .LBB0_486
